# grid barrier: the per-CU L1 invalidate is issued and waited for by wave 1 (parked at the final workgroup barrier anyway) instead of by wave 0 behind its arrival atomic
# baseline (speedup 1.0000x reference)
.Lgb1_done:
.LBB0_168:
	s_or_b64 exec, exec, s[0:1]
	v_readfirstlane_b32 s2, v209
	s_nop 0
	s_cmp_lg_u32 s2, 1
	s_cbranch_scc1 .Lgb1_noinv
	buffer_inv sc1
	s_waitcnt vmcnt(0)
.Lgb1_noinv:
	s_mov_b64 s[0:1], 0
	s_waitcnt lgkmcnt(0)
	s_barrier

.Lgb9_noinv:
	s_waitcnt lgkmcnt(0)
	s_barrier
